# MLA rotated loop edge, also the current-buffer offset and K fragment LDS address computed before the barrier
# baseline (speedup 1.0000x reference)
; #define LAS __attribute__((address_space(3)))
; #define MFMA32(a, b, c) __builtin_amdgcn_mfma_f32_32x32x16_bf16((a), (b), (c), 0, 0, 0)
; __device__ __forceinline__ void mla_unit2(LAS unsigned char* lds, const bf16_t* QB, const bf16_t* KB, const bf16_t* VT, bf16_t* OB, int b, int h, int qb, int wv) {
;     ...
;     for (int t = 0; t < ntiles; ++t) {
;         LAS unsigned char* cur = lds + (t & 1) * M2BUF;
;         { const int tn = (t + 1 < tl) ? t + 1 : tl;
;           ra = *(const u32x4*)(gKA + (size_t)tn * 64 * NQB); rc = *(const u32x4*)(gKC + (size_t)tn * 64 * NQB); rv = *(const u32x4*)(gV + tn * 64); }
;         if (t < nact) {
;             const int k0 = t * 64;
;             f32x16 sa0, sa1, sb0, sb1;
;             { const LAS unsigned char* kp = cur + r * MK_ROW + hh * 16;
; #pragma unroll
;               for (int i = 0; i < 16; ++i) { sa0[i] = 0.f; sa1[i] = 0.f; sb0[i] = 0.f; sb1[i] = 0.f; }
; #pragma unroll
;               for (int hf = 0; hf < 2; ++hf) {
;                   bf16x8 ka[3], kc[3];
; #pragma unroll
;                   for (int s = 0; s < 3; ++s) { ka[s] = *(const LAS bf16x8*)(kp + (3 * hf + s) * 32); kc[s] = *(const LAS bf16x8*)(kp + 32 * MK_ROW + (3 * hf + s) * 32); }
;                   __builtin_amdgcn_sched_barrier(0);
; #pragma unroll
;                   for (int s = 0; s < 3; ++s) { sa0 = MFMA32(ka[s], qa[3 * hf + s], sa0); sa1 = MFMA32(kc[s], qa[3 * hf + s], sa1); sb0 = MFMA32(ka[s], qbf[3 * hf + s], sb0); sb1 = MFMA32(kc[s], qbf[3 * hf + s], sb1); }
;                   __builtin_amdgcn_sched_barrier(0);
;               } }
.LBB0_661:
	s_add_i32 s76, s0, 1
	s_min_u32 s1, s76, s73
	s_mul_i32 s12, s1, 0x18000
	v_lshl_add_u64 v[192:193], v[200:201], 0, s[12:13]
	v_lshl_add_u64 v[194:195], v[202:203], 0, s[12:13]
	s_lshl_b32 s12, s1, 7
	v_lshl_add_u64 v[226:227], v[204:205], 0, s[12:13]
	s_bitcmp1_b32 s0, 0
	s_cselect_b32 s12, 0x5800, 0
	v_add3_u32 v215, s12, v209, v206
.Lmla_head:
	global_load_dwordx4 v[6:9], v[192:193], off
	s_nop 0
	global_load_dwordx4 v[2:5], v[194:195], off
	s_cmp_gt_i32 s0, s72
	global_load_dwordx4 v[10:13], v[226:227], off
	s_cbranch_scc1 .LBB0_676
	ds_read_b128 v[80:83], v215
	ds_read_b128 v[226:229], v215 offset:32
	ds_read_b128 v[84:87], v215 offset:6656
	ds_read_b128 v[230:233], v215 offset:64
	ds_read_b128 v[234:237], v215 offset:6688
	ds_read_b128 v[238:241], v215 offset:6720
	s_waitcnt vmcnt(14) lgkmcnt(5)
	v_mfma_f32_32x32x16_bf16 v[128:143], v[80:83], v[144:147], 0
	s_waitcnt lgkmcnt(3)
	v_mfma_f32_32x32x16_bf16 v[112:127], v[84:87], v[144:147], 0
	s_waitcnt vmcnt(5)
	v_mfma_f32_32x32x16_bf16 v[96:111], v[80:83], v[180:183], 0
	v_mfma_f32_32x32x16_bf16 v[80:95], v[84:87], v[180:183], 0
	v_mfma_f32_32x32x16_bf16 v[128:143], v[226:229], v[148:151], v[128:143]
	s_waitcnt lgkmcnt(1)
	v_mfma_f32_32x32x16_bf16 v[112:127], v[234:237], v[148:151], v[112:127]
	v_mfma_f32_32x32x16_bf16 v[96:111], v[226:229], v[156:159], v[96:111]
	v_mfma_f32_32x32x16_bf16 v[80:95], v[234:237], v[156:159], v[80:95]
	v_mfma_f32_32x32x16_bf16 v[128:143], v[230:233], v[152:155], v[128:143]
	s_waitcnt lgkmcnt(0)
	v_mfma_f32_32x32x16_bf16 v[112:127], v[238:241], v[152:155], v[112:127]
	v_mfma_f32_32x32x16_bf16 v[96:111], v[230:233], v[160:163], v[96:111]
	v_mfma_f32_32x32x16_bf16 v[80:95], v[238:241], v[160:163], v[80:95]
	ds_read_b128 v[226:229], v215 offset:96
	ds_read_b128 v[230:233], v215 offset:128
	ds_read_b128 v[234:237], v215 offset:6752
	ds_read_b128 v[238:241], v215 offset:160
	ds_read_b128 v[242:245], v215 offset:6784
	ds_read_b128 v[246:249], v215 offset:6816
	s_waitcnt lgkmcnt(5)
	v_mfma_f32_32x32x16_bf16 v[128:143], v[226:229], v[164:167], v[128:143]
	s_waitcnt lgkmcnt(3)
	v_mfma_f32_32x32x16_bf16 v[112:127], v[234:237], v[164:167], v[112:127]
	v_mfma_f32_32x32x16_bf16 v[96:111], v[226:229], v[172:175], v[96:111]
	v_mfma_f32_32x32x16_bf16 v[80:95], v[234:237], v[172:175], v[80:95]
	v_mfma_f32_32x32x16_bf16 v[128:143], v[230:233], v[168:171], v[128:143]
	s_waitcnt lgkmcnt(1)
	v_mfma_f32_32x32x16_bf16 v[112:127], v[242:245], v[168:171], v[112:127]
	v_mfma_f32_32x32x16_bf16 v[96:111], v[230:233], v[176:179], v[96:111]
	v_mfma_f32_32x32x16_bf16 v[80:95], v[242:245], v[176:179], v[80:95]
	s_waitcnt vmcnt(4)
	v_mfma_f32_32x32x16_bf16 v[128:143], v[238:241], v[184:187], v[128:143]
	s_waitcnt lgkmcnt(0)
	v_mfma_f32_32x32x16_bf16 v[112:127], v[246:249], v[184:187], v[112:127]
	s_waitcnt vmcnt(3)
	v_mfma_f32_32x32x16_bf16 v[96:111], v[238:241], v[188:191], v[96:111]
	v_mfma_f32_32x32x16_bf16 v[80:95], v[246:249], v[188:191], v[80:95]
	s_add_i32 s25, s71, 63
	s_cmp_le_i32 s25, s70
	s_nop 7
	s_cbranch_scc1 .Lmla_nomask
	s_cmp_eq_u32 s100, 0
	s_cbranch_scc1 .Lmla_m663
	s_mov_b32 s100, 0
	s_cmp_lg_u32 s71, 0
	s_cbranch_scc1 .Lmla_m663
	v_mov_b32_e32 v224, 0xff800000
	v_mov_b32_e32 v223, 0xff800000

; #define LAS __attribute__((address_space(3)))
; __device__ __forceinline__ void mla_unit2(LAS unsigned char* lds, const bf16_t* QB, const bf16_t* KB, const bf16_t* VT, bf16_t* OB, int b, int h, int qb, int wv) {
;     ...
;         { const int tn = (t + 1 < tl) ? t + 1 : tl;
;           ra = *(const u32x4*)(gKA + (size_t)tn * 64 * NQB); rc = *(const u32x4*)(gKC + (size_t)tn * 64 * NQB); rv = *(const u32x4*)(gV + tn * 64); }
;     ...
;         { LAS unsigned char* nxt = lds + ((t + 1) & 1) * M2BUF;
;           *(LAS u32x4*)(nxt + lKA) = ra; *(LAS u32x4*)(nxt + lKC) = rc; *(LAS u32x4*)(nxt + lV) = rv; }
;         __syncthreads();
.LBB0_676:
	s_bitcmp1_b32 s76, 0
	s_cselect_b32 s0, 0x5800, 0
	s_add_i32 s0, s0, 0
	v_add_u32_e32 v0, s0, v197
	s_waitcnt vmcnt(2)
	ds_write_b128 v0, v[6:9]
	v_add_u32_e32 v0, s0, v207
	s_add_i32 s71, s71, 64
	s_waitcnt vmcnt(1)
	ds_write_b128 v0, v[2:5]
	v_add_u32_e32 v0, s0, v208
	s_waitcnt vmcnt(0)
	ds_write_b128 v0, v[10:13] offset:13312
	s_mov_b32 s0, s76
	s_add_i32 s76, s0, 1
	s_min_u32 s1, s76, s73
	s_mul_i32 s12, s1, 0x18000
	v_lshl_add_u64 v[192:193], v[200:201], 0, s[12:13]
	v_lshl_add_u64 v[194:195], v[202:203], 0, s[12:13]
	s_lshl_b32 s12, s1, 7
	v_lshl_add_u64 v[226:227], v[204:205], 0, s[12:13]
	s_bitcmp1_b32 s0, 0
	s_cselect_b32 s12, 0x5800, 0
	v_add3_u32 v215, s12, v209, v206
	s_cmp_lg_u32 s75, s71
	s_waitcnt lgkmcnt(0)
	s_barrier
	s_cbranch_scc0 .LBB0_659
	s_branch .Lmla_head
